# v30 plus attention pass-prologue Q loads made row-contiguous (coalesced) and transposed to MFMA fragments through the wave-private LDS scratch
# baseline (speedup 1.0000x reference)
; #define LAS __attribute__((address_space(3)))
; template <bool DRY>
; __device__ __forceinline__ void attn_unit(const Args& a, LAS unsigned char* lds, int cidx, int h, int lane, int wave) {
;     ...
;         const int pi = pass >> 1, pr = wave + 8 * (pass & 1);
;         const int dsh = 2 * pi, res = pr >> (4 - dsh), sub = pr & ((16 >> dsh) - 1), L = S >> dsh;
;         const int sq0 = (Pu >> dsh) + 32 * sub, start = sq0 - 64;
;         const LAS float* btp = btw + pi * 192;
;         bf16x8 qf[2][4]; float rq[2]; int qpos[2];
; #pragma unroll
;         for (int gq = 0; gq < 2; ++gq) {
;             qpos[gq] = res + ((sq0 + 16 * gq + fr) << dsh);
;             const unsigned qtok = (unsigned)(seq_start + qpos[gq]);
;             const unsigned qoff = (qtok * AW + h * 128 + fq * 8) * 2u;
; #pragma unroll
;             for (int s = 0; s < 4; ++s) qf[gq][s] = *(const bf16x8*)((const char*)Qb + qoff + s * 64);
;             rq[gq] = *(const float*)((const char*)ssq + ((unsigned)(h * 4) * MTOK + qtok) * 4u);
;         }
;         f32x4 o[2][8];
; #pragma unroll
;         for (int gq = 0; gq < 2; ++gq)
; #pragma unroll
;             for (int c = 0; c < 8; ++c) o[gq][c] = (f32x4){0.f, 0.f, 0.f, 0.f};
;         float den[2] = {0.f, 0.f};
;         u32x4 kreg[8], vreg[8]; float rks;
;     ...
;         ATT_LOAD(0);
.LBB0_596:
	s_lshl_b32 s6, s51, 3
	s_and_b32 s6, s6, 8
	s_and_b32 s53, s51, 6
	s_add_i32 s6, s6, s78
	s_sub_i32 s7, 4, s53
	s_lshr_b32 s56, s6, s7
	s_lshr_b32 s7, 16, s53
	s_add_i32 s7, s7, -1
	s_and_b32 s6, s6, s7
	s_ashr_i32 s7, s50, s53
	s_lshl_b32 s6, s6, 5
	s_add_i32 s6, s6, s7
	v_add_u32_e32 v0, s6, v163
	v_lshlrev_b32_e32 v1, s53, v0
	v_add_u32_e32 v190, s56, v1
	v_add_lshl_u32 v0, v0, 16, s53
	v_add_u32_e32 v1, s47, v190
	v_add_u32_e32 v189, s56, v0
	v_lshlrev_b32_e32 v192, 12, v1
	v_add_u32_e32 v0, s47, v189
	v_add_u32_e32 v2, v192, v188
	v_lshlrev_b32_e32 v191, 12, v0
	s_add_i32 s99, s56, s47
	v_add_u32_e32 v252, s6, v165
	v_add_u32_e32 v253, 0, v252
	v_lshlrev_b32_e32 v253, s53, v253
	v_add_u32_e32 v253, s99, v253
	v_lshl_or_b32 v253, v253, 12, v186
	global_load_dwordx4 v[64:67], v253, s[26:27]
	v_add_u32_e32 v253, 4, v252
	v_lshlrev_b32_e32 v253, s53, v253
	v_add_u32_e32 v253, s99, v253
	v_lshl_or_b32 v253, v253, 12, v186
	global_load_dwordx4 v[68:71], v253, s[26:27]
	v_add_u32_e32 v253, 8, v252
	v_lshlrev_b32_e32 v253, s53, v253
	v_add_u32_e32 v253, s99, v253
	v_lshl_or_b32 v253, v253, 12, v186
	global_load_dwordx4 v[72:75], v253, s[26:27]
	v_add_u32_e32 v253, 12, v252
	v_lshlrev_b32_e32 v253, s53, v253
	v_add_u32_e32 v253, s99, v253
	v_lshl_or_b32 v253, v253, 12, v186
	global_load_dwordx4 v[76:79], v253, s[26:27]
	v_add_u32_e32 v253, 16, v252
	v_lshlrev_b32_e32 v253, s53, v253
	v_add_u32_e32 v253, s99, v253
	v_lshl_or_b32 v253, v253, 12, v186
	global_load_dwordx4 v[80:83], v253, s[26:27]
	v_add_u32_e32 v253, 20, v252
	v_lshlrev_b32_e32 v253, s53, v253
	v_add_u32_e32 v253, s99, v253
	v_lshl_or_b32 v253, v253, 12, v186
	global_load_dwordx4 v[84:87], v253, s[26:27]
	v_add_u32_e32 v253, 24, v252
	v_lshlrev_b32_e32 v253, s53, v253
	v_add_u32_e32 v253, s99, v253
	v_lshl_or_b32 v253, v253, 12, v186
	global_load_dwordx4 v[88:91], v253, s[26:27]
	v_add_u32_e32 v253, 28, v252
	v_lshlrev_b32_e32 v253, s53, v253
	v_add_u32_e32 v253, s99, v253
	v_lshl_or_b32 v253, v253, 12, v186
	global_load_dwordx4 v[92:95], v253, s[26:27]
	v_add_lshl_u32 v1, v1, s44, 2
	v_add_u32_e32 v2, v191, v188
	v_add_lshl_u32 v0, v0, s44, 2
	s_sub_i32 s7, s6, 64
	s_lshr_b32 s54, s45, s53
	global_load_dword v193, v1, s[10:11]
	global_load_dword v194, v0, s[10:11]
	v_add_u32_e32 v0, s7, v165
	s_add_i32 s55, s54, -1
	v_min_i32_e32 v1, s55, v0
	v_cmp_lt_i32_e32 vcc, -1, v0
	s_add_i32 s56, s56, s47
	s_add_i32 s57, s46, s56
	v_cndmask_b32_e32 v1, 0, v1, vcc
	v_lshlrev_b32_e32 v1, s53, v1
	v_add_u32_e32 v1, s56, v1
	v_lshl_or_b32 v1, v1, 12, v186
	global_load_dwordx4 v[96:99], v1, s[12:13]
	global_load_dwordx4 v[100:103], v1, s[28:29]
	v_add_u32_e32 v1, 4, v0
	v_min_i32_e32 v1, s55, v1
	v_cmp_lt_i32_e32 vcc, -5, v0
	s_lshr_b32 s52, s51, 1
	v_mov_b32_e32 v40, 0
	v_cndmask_b32_e32 v1, 0, v1, vcc
	v_lshlrev_b32_e32 v1, s53, v1
	v_add_u32_e32 v1, s56, v1
	v_lshl_or_b32 v1, v1, 12, v186
	global_load_dwordx4 v[104:107], v1, s[12:13]
	global_load_dwordx4 v[108:111], v1, s[28:29]
	v_add_u32_e32 v1, 8, v0
	v_min_i32_e32 v1, s55, v1
	v_cmp_lt_i32_e32 vcc, -9, v0
	s_mov_b32 s64, 0
	v_add_u32_e32 v195, s6, v173
	v_cndmask_b32_e32 v1, 0, v1, vcc
	v_lshlrev_b32_e32 v1, s53, v1
	v_add_u32_e32 v1, s56, v1
	v_lshl_or_b32 v1, v1, 12, v186
	global_load_dwordx4 v[112:115], v1, s[12:13]
	global_load_dwordx4 v[116:119], v1, s[28:29]
	v_add_u32_e32 v1, 12, v0
	v_min_i32_e32 v1, s55, v1
	v_cmp_lt_i32_e32 vcc, -13, v0
	v_add_u32_e32 v196, s6, v165
	v_add_u32_e32 v197, s6, v174
	v_cndmask_b32_e32 v1, 0, v1, vcc
	v_lshlrev_b32_e32 v1, s53, v1
	v_add_u32_e32 v1, s56, v1
	v_lshl_or_b32 v1, v1, 12, v186
	global_load_dwordx4 v[120:123], v1, s[12:13]
	global_load_dwordx4 v[124:127], v1, s[28:29]
	v_add_u32_e32 v1, 16, v0
	v_min_i32_e32 v1, s55, v1
	v_cmp_lt_i32_e32 vcc, s39, v0
	v_mov_b32_e32 v41, v40
	v_mov_b32_e32 v42, v40
	v_cndmask_b32_e32 v1, 0, v1, vcc
	v_lshlrev_b32_e32 v1, s53, v1
	v_add_u32_e32 v1, s56, v1
	v_lshl_or_b32 v1, v1, 12, v186
	global_load_dwordx4 v[128:131], v1, s[12:13]
	global_load_dwordx4 v[132:135], v1, s[28:29]
	v_add_u32_e32 v1, 20, v0
	v_min_i32_e32 v1, s55, v1
	v_cmp_lt_i32_e32 vcc, s40, v0
	v_mov_b32_e32 v43, v40
	v_mov_b32_e32 v60, v40
	v_cndmask_b32_e32 v1, 0, v1, vcc
	v_lshlrev_b32_e32 v1, s53, v1
	v_add_u32_e32 v1, s56, v1
	v_lshl_or_b32 v1, v1, 12, v186
	global_load_dwordx4 v[136:139], v1, s[12:13]
	global_load_dwordx4 v[140:143], v1, s[28:29]
	v_add_u32_e32 v1, 24, v0
	v_min_i32_e32 v1, s55, v1
	v_cmp_lt_i32_e32 vcc, s41, v0
	v_mov_b32_e32 v61, v40
	v_mov_b32_e32 v62, v40
	v_cndmask_b32_e32 v1, 0, v1, vcc
	v_lshlrev_b32_e32 v1, s53, v1
	v_add_u32_e32 v1, s56, v1
	v_lshl_or_b32 v1, v1, 12, v186
	global_load_dwordx4 v[144:147], v1, s[12:13]
	global_load_dwordx4 v[148:151], v1, s[28:29]
	v_add_u32_e32 v1, 28, v0
	v_min_i32_e32 v1, s55, v1
	v_cmp_lt_i32_e32 vcc, s42, v0
	v_mov_b32_e32 v63, v40
	v_mov_b32_e32 v56, v40
	v_cndmask_b32_e32 v0, 0, v1, vcc
	v_lshlrev_b32_e32 v0, s53, v0
	v_add_u32_e32 v0, s56, v0
	v_lshl_or_b32 v0, v0, 12, v186
	global_load_dwordx4 v[152:155], v0, s[12:13]
	global_load_dwordx4 v[156:159], v0, s[28:29]
	v_add_u32_e32 v0, s7, v168
	v_min_i32_e32 v1, s55, v0
	v_cmp_lt_i32_e32 vcc, -1, v0
	s_mul_i32 s7, s52, 0x300
	v_add_u32_e32 v199, s7, v175
	v_cndmask_b32_e32 v0, 0, v1, vcc
	v_lshlrev_b32_e32 v0, s53, v0
	v_add_lshl_u32 v0, v0, s57, 2
	global_load_dword v198, v0, s[10:11]
	v_mov_b32_e32 v57, v40
	v_mov_b32_e32 v58, v40
	v_mov_b32_e32 v59, v40
	v_mov_b32_e32 v52, v40
	v_mov_b32_e32 v53, v40
	v_mov_b32_e32 v54, v40
	v_mov_b32_e32 v55, v40
	v_mov_b32_e32 v48, v40
	v_mov_b32_e32 v49, v40
	v_mov_b32_e32 v50, v40
	v_mov_b32_e32 v51, v40
	v_mov_b32_e32 v44, v40
	v_mov_b32_e32 v45, v40
	v_mov_b32_e32 v46, v40
	v_mov_b32_e32 v47, v40
	v_mov_b32_e32 v36, v40
	v_mov_b32_e32 v37, v40
	v_mov_b32_e32 v38, v40
	v_mov_b32_e32 v39, v40
	v_mov_b32_e32 v32, v40
	v_mov_b32_e32 v33, v40
	v_mov_b32_e32 v34, v40
	v_mov_b32_e32 v35, v40
	v_mov_b32_e32 v28, v40
	v_mov_b32_e32 v29, v40
	v_mov_b32_e32 v30, v40
	v_mov_b32_e32 v31, v40
	v_mov_b32_e32 v24, v40
	v_mov_b32_e32 v25, v40
	v_mov_b32_e32 v26, v40
	v_mov_b32_e32 v27, v40
	v_mov_b32_e32 v20, v40
	v_mov_b32_e32 v21, v40
	v_mov_b32_e32 v22, v40
	v_mov_b32_e32 v23, v40
	v_mov_b32_e32 v16, v40
	v_mov_b32_e32 v17, v40
	v_mov_b32_e32 v18, v40
	v_mov_b32_e32 v19, v40
	v_mov_b32_e32 v12, v40
	v_mov_b32_e32 v13, v40
	v_mov_b32_e32 v14, v40
	v_mov_b32_e32 v15, v40
	v_mov_b32_e32 v8, v40
	v_mov_b32_e32 v9, v40
	v_mov_b32_e32 v10, v40
	v_mov_b32_e32 v11, v40
	v_mov_b32_e32 v4, v40
	v_mov_b32_e32 v5, v40
	v_mov_b32_e32 v6, v40
	v_mov_b32_e32 v7, v40
	v_mov_b32_e32 v0, v40
	v_mov_b32_e32 v1, v40
	v_mov_b32_e32 v2, v40
	v_mov_b32_e32 v3, v40
	v_mov_b32_e32 v160, v40
	v_mov_b32_e32 v161, v40
	s_mul_i32 s98, s78, 0x4a00
	v_mul_u32_u24_e32 v250, 0x110, v165
	v_add3_u32 v250, v250, v167, s98
	v_mul_u32_u24_e32 v251, 0x110, v163
	v_add3_u32 v251, v251, v169, s98
	s_waitcnt vmcnt(19)
; template <bool DRY>
; __device__ __forceinline__ void attn_unit(const Args& a, LAS unsigned char* lds, int cidx, int h, int lane, int wave) {
;     ...
;         for (int gq = 0; gq < 2; ++gq) {
;             qpos[gq] = res + ((sq0 + 16 * gq + fr) << dsh);
;             const unsigned qtok = (unsigned)(seq_start + qpos[gq]);
;             const unsigned qoff = (qtok * AW + h * 128 + fq * 8) * 2u;
; #pragma unroll
;             for (int s = 0; s < 4; ++s) qf[gq][s] = *(const bf16x8*)((const char*)Qb + qoff + s * 64);
	ds_write_b128 v250, v[64:67]
	ds_write_b128 v250, v[68:71] offset:1088
	ds_write_b128 v250, v[72:75] offset:2176
	ds_write_b128 v250, v[76:79] offset:3264
	ds_write_b128 v250, v[80:83] offset:4352
	ds_write_b128 v250, v[84:87] offset:5440
	ds_write_b128 v250, v[88:91] offset:6528
	ds_write_b128 v250, v[92:95] offset:7616
	ds_read_b128 v[64:67], v251
	ds_read_b128 v[68:71], v251 offset:64
	ds_read_b128 v[72:75], v251 offset:128
	ds_read_b128 v[76:79], v251 offset:192
	ds_read_b128 v[80:83], v251 offset:4352
	ds_read_b128 v[84:87], v251 offset:4416
	ds_read_b128 v[88:91], v251 offset:4480
	ds_read_b128 v[92:95], v251 offset:4544
	s_branch .LBB0_598
